# NSA top-k selection loop: 8 independent wave-wide argmax reductions batched per hop (6 LDS round trips per round instead of 18)
# baseline (speedup 1.0000x reference)
.LBB0_1810:
	v_cmp_gt_u32_e32 vcc, v44, v45
	s_nop 1
	v_cndmask_b32_e32 v54, v45, v44, vcc
	v_cndmask_b32_e64 v53, 0, 1, vcc
	v_cmp_gt_u32_e32 vcc, v42, v54
	s_nop 1
	v_cndmask_b32_e32 v54, v54, v42, vcc
	v_cndmask_b32_e64 v53, v53, 2, vcc
	v_cmp_gt_u32_e32 vcc, v41, v54
	s_nop 1
	v_cndmask_b32_e64 v62, v53, 3, vcc
	v_cndmask_b32_e32 v83, v54, v41, vcc
	v_cmp_gt_u32_e32 vcc, v39, v40
	s_nop 1
	v_cndmask_b32_e32 v54, v40, v39, vcc
	v_cndmask_b32_e64 v53, 0, 1, vcc
	v_cmp_gt_u32_e32 vcc, v37, v54
	s_nop 1
	v_cndmask_b32_e32 v54, v54, v37, vcc
	v_cndmask_b32_e64 v53, v53, 2, vcc
	v_cmp_gt_u32_e32 vcc, v36, v54
	s_nop 1
	v_cndmask_b32_e64 v67, v53, 3, vcc
	v_cndmask_b32_e32 v72, v54, v36, vcc
	v_cmp_gt_u32_e32 vcc, v34, v35
	s_nop 1
	v_cndmask_b32_e32 v54, v35, v34, vcc
	v_cndmask_b32_e64 v53, 0, 1, vcc
	v_cmp_gt_u32_e32 vcc, v32, v54
	s_nop 1
	v_cndmask_b32_e32 v54, v54, v32, vcc
	v_cndmask_b32_e64 v53, v53, 2, vcc
	v_cmp_gt_u32_e32 vcc, v31, v54
	s_nop 1
	v_cndmask_b32_e64 v65, v53, 3, vcc
	v_cndmask_b32_e32 v69, v54, v31, vcc
	v_cmp_gt_u32_e32 vcc, v29, v30
	s_nop 1
	v_cndmask_b32_e32 v54, v30, v29, vcc
	v_cndmask_b32_e64 v53, 0, 1, vcc
	v_cmp_gt_u32_e32 vcc, v27, v54
	s_nop 1
	v_cndmask_b32_e32 v54, v54, v27, vcc
	v_cndmask_b32_e64 v53, v53, 2, vcc
	v_cmp_gt_u32_e32 vcc, v26, v54
	s_nop 1
	v_cndmask_b32_e64 v61, v53, 3, vcc
	v_cndmask_b32_e32 v64, v54, v26, vcc
	v_cmp_gt_u32_e32 vcc, v24, v25
	s_nop 1
	v_cndmask_b32_e32 v54, v25, v24, vcc
	v_cndmask_b32_e64 v53, 0, 1, vcc
	v_cmp_gt_u32_e32 vcc, v22, v54
	s_nop 1
	v_cndmask_b32_e32 v54, v54, v22, vcc
	v_cndmask_b32_e64 v53, v53, 2, vcc
	v_cmp_gt_u32_e32 vcc, v21, v54
	s_nop 1
	v_cndmask_b32_e64 v59, v53, 3, vcc
	v_cndmask_b32_e32 v60, v54, v21, vcc
	v_cmp_gt_u32_e32 vcc, v19, v20
	s_nop 1
	v_cndmask_b32_e32 v54, v20, v19, vcc
	v_cndmask_b32_e64 v53, 0, 1, vcc
	v_cmp_gt_u32_e32 vcc, v17, v54
	s_nop 1
	v_cndmask_b32_e32 v54, v54, v17, vcc
	v_cndmask_b32_e64 v53, v53, 2, vcc
	v_cmp_gt_u32_e32 vcc, v15, v54
	s_nop 1
	v_cndmask_b32_e64 v56, v53, 3, vcc
	v_cndmask_b32_e32 v58, v54, v15, vcc
	v_cmp_gt_u32_e32 vcc, v12, v13
	s_nop 1
	v_cndmask_b32_e32 v54, v13, v12, vcc
	v_cndmask_b32_e64 v53, 0, 1, vcc
	v_cmp_gt_u32_e32 vcc, v11, v54
	s_nop 1
	v_cndmask_b32_e32 v55, v54, v11, vcc
	v_cndmask_b32_e64 v53, v53, 2, vcc
	v_cmp_gt_u32_e32 vcc, v10, v55
	s_nop 1
	v_cndmask_b32_e64 v54, v53, 3, vcc
	v_cndmask_b32_e32 v55, v55, v10, vcc
	v_cmp_gt_u32_e32 vcc, v8, v9
	s_nop 1
	v_cndmask_b32_e32 v57, v9, v8, vcc
	v_cndmask_b32_e64 v53, 0, 1, vcc
	v_cmp_gt_u32_e32 vcc, v6, v57
	s_nop 1
	v_cndmask_b32_e64 v84, v53, 2, vcc
	v_cndmask_b32_e32 v53, v57, v6, vcc
	v_cmp_gt_u32_e32 vcc, v5, v53
	s_nop 1
	v_cndmask_b32_e32 v53, v53, v5, vcc
	v_cndmask_b32_e64 v63, v84, 3, vcc
	ds_bpermute_b32 v84, v46, v83
	ds_bpermute_b32 v82, v46, v72
	ds_bpermute_b32 v80, v46, v69
	ds_bpermute_b32 v78, v46, v64
	ds_bpermute_b32 v76, v46, v60
	ds_bpermute_b32 v74, v46, v58
	ds_bpermute_b32 v71, v46, v55
	ds_bpermute_b32 v68, v46, v53
	s_waitcnt lgkmcnt(0)
	v_max_u32_e32 v57, v84, v83
	v_max_u32_e32 v81, v82, v72
	v_max_u32_e32 v79, v80, v69
	v_max_u32_e32 v77, v78, v64
	v_max_u32_e32 v75, v76, v60
	v_max_u32_e32 v73, v74, v58
	v_max_u32_e32 v70, v71, v55
	v_max_u32_e32 v66, v68, v53
	ds_bpermute_b32 v84, v47, v57
	ds_bpermute_b32 v82, v47, v81
	ds_bpermute_b32 v80, v47, v79
	ds_bpermute_b32 v78, v47, v77
	ds_bpermute_b32 v76, v47, v75
	ds_bpermute_b32 v74, v47, v73
	ds_bpermute_b32 v71, v47, v70
	ds_bpermute_b32 v68, v47, v66
	s_waitcnt lgkmcnt(0)
	v_max_u32_e32 v57, v84, v57
	v_max_u32_e32 v81, v82, v81
	v_max_u32_e32 v79, v80, v79
	v_max_u32_e32 v77, v78, v77
	v_max_u32_e32 v75, v76, v75
	v_max_u32_e32 v73, v74, v73
	v_max_u32_e32 v70, v71, v70
	v_max_u32_e32 v66, v68, v66
	ds_bpermute_b32 v84, v48, v57
	ds_bpermute_b32 v82, v48, v81
	ds_bpermute_b32 v80, v48, v79
	ds_bpermute_b32 v78, v48, v77
	ds_bpermute_b32 v76, v48, v75
	ds_bpermute_b32 v74, v48, v73
	ds_bpermute_b32 v71, v48, v70
	ds_bpermute_b32 v68, v48, v66
	s_waitcnt lgkmcnt(0)
	v_max_u32_e32 v57, v84, v57
	v_max_u32_e32 v81, v82, v81
	v_max_u32_e32 v79, v80, v79
	v_max_u32_e32 v77, v78, v77
	v_max_u32_e32 v75, v76, v75
	v_max_u32_e32 v73, v74, v73
	v_max_u32_e32 v70, v71, v70
	v_max_u32_e32 v66, v68, v66
	ds_bpermute_b32 v84, v49, v57
	ds_bpermute_b32 v82, v49, v81
	ds_bpermute_b32 v80, v49, v79
	ds_bpermute_b32 v78, v49, v77
	ds_bpermute_b32 v76, v49, v75
	ds_bpermute_b32 v74, v49, v73
	ds_bpermute_b32 v71, v49, v70
	ds_bpermute_b32 v68, v49, v66
	s_waitcnt lgkmcnt(0)
	v_max_u32_e32 v57, v84, v57
	v_max_u32_e32 v81, v82, v81
	v_max_u32_e32 v79, v80, v79
	v_max_u32_e32 v77, v78, v77
	v_max_u32_e32 v75, v76, v75
	v_max_u32_e32 v73, v74, v73
	v_max_u32_e32 v70, v71, v70
	v_max_u32_e32 v66, v68, v66
	ds_bpermute_b32 v84, v50, v57
	ds_bpermute_b32 v82, v50, v81
	ds_bpermute_b32 v80, v50, v79
	ds_bpermute_b32 v78, v50, v77
	ds_bpermute_b32 v76, v50, v75
	ds_bpermute_b32 v74, v50, v73
	ds_bpermute_b32 v71, v50, v70
	ds_bpermute_b32 v68, v50, v66
	s_waitcnt lgkmcnt(0)
	v_max_u32_e32 v57, v84, v57
	v_max_u32_e32 v81, v82, v81
	v_max_u32_e32 v79, v80, v79
	v_max_u32_e32 v77, v78, v77
	v_max_u32_e32 v75, v76, v75
	v_max_u32_e32 v73, v74, v73
	v_max_u32_e32 v70, v71, v70
	v_max_u32_e32 v66, v68, v66
	ds_bpermute_b32 v84, v51, v57
	ds_bpermute_b32 v82, v51, v81
	ds_bpermute_b32 v80, v51, v79
	ds_bpermute_b32 v78, v51, v77
	ds_bpermute_b32 v76, v51, v75
	ds_bpermute_b32 v74, v51, v73
	ds_bpermute_b32 v71, v51, v70
	ds_bpermute_b32 v68, v51, v66
	s_waitcnt lgkmcnt(7)
	v_max_u32_e32 v57, v84, v57
	v_cmp_eq_u32_e32 vcc, v83, v57
	v_cmp_ne_u32_e64 s[2:3], 0, v57
	s_and_b64 s[4:5], s[2:3], vcc
	s_and_saveexec_b64 s[2:3], s[4:5]
	v_cmp_ne_u32_e32 vcc, 0, v62
	v_lshl_or_b32 v43, 1, v62, v43
	s_nop 0
	v_cndmask_b32_e32 v45, 0, v45, vcc
	v_cmp_ne_u32_e32 vcc, 1, v62
	s_nop 1
	v_cndmask_b32_e32 v44, 0, v44, vcc
	v_cmp_ne_u32_e32 vcc, 2, v62
	s_nop 1
	v_cndmask_b32_e32 v42, 0, v42, vcc
	v_cmp_ne_u32_e32 vcc, 3, v62
	s_nop 1
	v_cndmask_b32_e32 v41, 0, v41, vcc
	s_or_b64 exec, exec, s[2:3]
	s_waitcnt lgkmcnt(0)
	v_max_u32_e32 v62, v82, v81
	v_cmp_eq_u32_e32 vcc, v72, v62
	v_cmp_ne_u32_e64 s[2:3], 0, v62
	s_and_b64 s[4:5], s[2:3], vcc
	s_and_saveexec_b64 s[2:3], s[4:5]
	v_cmp_ne_u32_e32 vcc, 0, v67
	v_lshl_or_b32 v38, 1, v67, v38
	s_nop 0
	v_cndmask_b32_e32 v40, 0, v40, vcc
	v_cmp_ne_u32_e32 vcc, 1, v67
	s_nop 1
	v_cndmask_b32_e32 v39, 0, v39, vcc
	v_cmp_ne_u32_e32 vcc, 2, v67
	s_nop 1
	v_cndmask_b32_e32 v37, 0, v37, vcc
	v_cmp_ne_u32_e32 vcc, 3, v67
	s_nop 1
	v_cndmask_b32_e32 v36, 0, v36, vcc
	s_or_b64 exec, exec, s[2:3]
	v_max_u32_e32 v67, v80, v79
	v_cmp_eq_u32_e32 vcc, v69, v67
	v_cmp_ne_u32_e64 s[2:3], 0, v67
	s_and_b64 s[4:5], s[2:3], vcc
	s_and_saveexec_b64 s[2:3], s[4:5]
	v_cmp_ne_u32_e32 vcc, 0, v65
	v_lshl_or_b32 v33, 1, v65, v33
	s_nop 0
	v_cndmask_b32_e32 v35, 0, v35, vcc
	v_cmp_ne_u32_e32 vcc, 1, v65
	s_nop 1
	v_cndmask_b32_e32 v34, 0, v34, vcc
	v_cmp_ne_u32_e32 vcc, 2, v65
	s_nop 1
	v_cndmask_b32_e32 v32, 0, v32, vcc
	v_cmp_ne_u32_e32 vcc, 3, v65
	s_nop 1
	v_cndmask_b32_e32 v31, 0, v31, vcc
	s_or_b64 exec, exec, s[2:3]
	v_max_u32_e32 v65, v78, v77
	v_cmp_eq_u32_e32 vcc, v64, v65
	v_cmp_ne_u32_e64 s[2:3], 0, v65
	s_and_b64 s[4:5], s[2:3], vcc
	s_and_saveexec_b64 s[2:3], s[4:5]
	v_cmp_ne_u32_e32 vcc, 0, v61
	v_lshl_or_b32 v28, 1, v61, v28
	s_nop 0
	v_cndmask_b32_e32 v30, 0, v30, vcc
	v_cmp_ne_u32_e32 vcc, 1, v61
	s_nop 1
	v_cndmask_b32_e32 v29, 0, v29, vcc
	v_cmp_ne_u32_e32 vcc, 2, v61
	s_nop 1
	v_cndmask_b32_e32 v27, 0, v27, vcc
	v_cmp_ne_u32_e32 vcc, 3, v61
	s_nop 1
	v_cndmask_b32_e32 v26, 0, v26, vcc
	s_or_b64 exec, exec, s[2:3]
	v_max_u32_e32 v61, v76, v75
	v_cmp_eq_u32_e32 vcc, v60, v61
	v_cmp_ne_u32_e64 s[2:3], 0, v61
	s_and_b64 s[4:5], s[2:3], vcc
	s_and_saveexec_b64 s[2:3], s[4:5]
	v_cmp_ne_u32_e32 vcc, 0, v59
	v_lshl_or_b32 v23, 1, v59, v23
	s_nop 0
	v_cndmask_b32_e32 v25, 0, v25, vcc
	v_cmp_ne_u32_e32 vcc, 1, v59
	s_nop 1
	v_cndmask_b32_e32 v24, 0, v24, vcc
	v_cmp_ne_u32_e32 vcc, 2, v59
	s_nop 1
	v_cndmask_b32_e32 v22, 0, v22, vcc
	v_cmp_ne_u32_e32 vcc, 3, v59
	s_nop 1
	v_cndmask_b32_e32 v21, 0, v21, vcc
	s_or_b64 exec, exec, s[2:3]
	v_max_u32_e32 v59, v74, v73
	v_cmp_eq_u32_e32 vcc, v58, v59
	v_cmp_ne_u32_e64 s[2:3], 0, v59
	s_and_b64 s[4:5], s[2:3], vcc
	s_and_saveexec_b64 s[2:3], s[4:5]
	v_cmp_ne_u32_e32 vcc, 0, v56
	v_lshl_or_b32 v18, 1, v56, v18
	s_nop 0
	v_cndmask_b32_e32 v20, 0, v20, vcc
	v_cmp_ne_u32_e32 vcc, 1, v56
	s_nop 1
	v_cndmask_b32_e32 v19, 0, v19, vcc
	v_cmp_ne_u32_e32 vcc, 2, v56
	s_nop 1
	v_cndmask_b32_e32 v17, 0, v17, vcc
	v_cmp_ne_u32_e32 vcc, 3, v56
	s_nop 1
	v_cndmask_b32_e32 v15, 0, v15, vcc
	s_or_b64 exec, exec, s[2:3]
	v_max_u32_e32 v56, v71, v70
	v_cmp_eq_u32_e32 vcc, v55, v56
	v_cmp_ne_u32_e64 s[2:3], 0, v56
	s_and_b64 s[4:5], s[2:3], vcc
	s_and_saveexec_b64 s[2:3], s[4:5]
	v_cmp_ne_u32_e32 vcc, 0, v54
	v_lshl_or_b32 v14, 1, v54, v14
	s_nop 0
	v_cndmask_b32_e32 v13, 0, v13, vcc
	v_cmp_ne_u32_e32 vcc, 1, v54
	s_nop 1
	v_cndmask_b32_e32 v12, 0, v12, vcc
	v_cmp_ne_u32_e32 vcc, 2, v54
	s_nop 1
	v_cndmask_b32_e32 v11, 0, v11, vcc
	v_cmp_ne_u32_e32 vcc, 3, v54
	s_nop 1
	v_cndmask_b32_e32 v10, 0, v10, vcc
	s_or_b64 exec, exec, s[2:3]
	v_max_u32_e32 v54, v68, v66
	v_cmp_eq_u32_e32 vcc, v53, v54
	v_cmp_ne_u32_e64 s[2:3], 0, v54
	s_and_b64 s[2:3], vcc, s[2:3]
	s_and_saveexec_b64 s[4:5], s[2:3]
	s_xor_b64 s[2:3], exec, s[4:5]
	s_cbranch_execz .LBB0_1809
	v_cmp_ne_u32_e32 vcc, 0, v63
	v_lshl_or_b32 v7, 1, v63, v7
	s_nop 0
	v_cndmask_b32_e32 v9, 0, v9, vcc
	v_cmp_ne_u32_e32 vcc, 1, v63
	s_nop 1
	v_cndmask_b32_e32 v8, 0, v8, vcc
	v_cmp_ne_u32_e32 vcc, 2, v63
	s_nop 1
	v_cndmask_b32_e32 v6, 0, v6, vcc
	v_cmp_ne_u32_e32 vcc, 3, v63
	s_nop 1
	v_cndmask_b32_e32 v5, 0, v5, vcc
	s_branch .LBB0_1809
